# mixer phase Y stores (attention / HGRN-combine epilogue dwordx2) made write-through (sc1)
# baseline (speedup 1.0000x reference)
; DI float bflo(unsigned w) { return __uint_as_float(w << 16); }
; DI float bfhi(unsigned w) { return __uint_as_float(w & 0xffff0000u); }
; template <int MODE> ...
;     ...
;   float linv[2][2];
; #pragma unroll
;   for (int tt = 0; tt < 2; ++tt)
; #pragma unroll
;     for (int hh = 0; hh < 2; ++hh) {
;       float lt = lsum[tt][hh];
;       lt += __shfl_xor(lt, 16);
;       lt += __shfl_xor(lt, 32);
;       if (has_sink) lt += __builtin_amdgcn_exp2f((hh ? sink1 : sink0) + nbias[tt][hh]);
;       linv[tt][hh] = 1.f / lt;
;     }
;   if constexpr (MODE == 0) {
;     uint2 gg[2][2][4];
; #pragma unroll
;     for (int tt = 0; tt < 2; ++tt)
; #pragma unroll
;       for (int hh = 0; hh < 2; ++hh)
; #pragma unroll
;         for (int dt = 0; dt < 4; ++dt)
;           gg[tt][hh][dt] = *(const uint2*)(p.G + (size_t)(yrow0 + w * 32 + tt * 16 + r) * 1024 + ycol0 + hh * 64 + dt * 16 + g * 4);
; #pragma unroll
;     for (int tt = 0; tt < 2; ++tt) {
;       const int row = yrow0 + w * 32 + tt * 16 + r;
; #pragma unroll
;       for (int hh = 0; hh < 2; ++hh)
; #pragma unroll
;         for (int dt = 0; dt < 4; ++dt) {
;           const int col = ycol0 + hh * 64 + dt * 16 + g * 4;
;           const float li = linv[tt][hh];
;           const uint2 gq = gg[tt][hh][dt];
;           uint2 o;
;           o.x = pack2(O[tt][hh][dt][0] * li * bflo(gq.x), O[tt][hh][dt][1] * li * bfhi(gq.x));
;           o.y = pack2(O[tt][hh][dt][2] * li * bflo(gq.y), O[tt][hh][dt][3] * li * bfhi(gq.y));
;           *(uint2*)(p.H + (size_t)row * 1024 + col) = o;
.LBB0_878:
	v_and_b32_e32 v3, 64, v226
	v_xor_b32_e32 v0, 16, v226
	v_add_u32_e32 v3, 64, v3
	v_cmp_lt_i32_e32 vcc, v0, v3
	v_xor_b32_e32 v68, 32, v226
	v_add_f32_e32 v2, v172, v2
	v_cndmask_b32_e32 v0, v226, v0, vcc
	v_lshlrev_b32_e32 v0, 2, v0
	v_cmp_lt_i32_e32 vcc, v68, v3
	v_exp_f32_e32 v2, v2
	s_mov_b32 s45, s3
	v_cndmask_b32_e32 v3, v226, v68, vcc
	ds_bpermute_b32 v68, v0, v188
	v_lshlrev_b32_e32 v3, 2, v3
	s_mov_b64 s[56:57], s[74:75]
	v_readlane_b32 s68, v255, 28
	v_readlane_b32 s69, v255, 29
	s_waitcnt lgkmcnt(0)
	v_add_f32_e32 v68, v188, v68
	ds_bpermute_b32 v69, v3, v68
	v_readlane_b32 s74, v255, 34
	v_readlane_b32 s75, v255, 35
	v_readlane_b32 s70, v255, 30
	v_readlane_b32 s71, v255, 31
	s_waitcnt lgkmcnt(0)
	v_add_f32_e32 v68, v68, v69
	v_add_f32_e32 v69, v172, v180
	v_exp_f32_e32 v69, v69
	v_readlane_b32 s72, v255, 32
	v_readlane_b32 s73, v255, 33
	s_mov_b64 s[74:75], s[56:57]
	v_add_f32_e32 v69, v69, v68
	v_cndmask_b32_e64 v68, v68, v69, s[40:41]
	ds_bpermute_b32 v69, v0, v189
	s_waitcnt lgkmcnt(0)
	v_add_f32_e32 v69, v189, v69
	ds_bpermute_b32 v70, v3, v69
	s_waitcnt lgkmcnt(0)
	v_add_f32_e32 v69, v69, v70
	v_add_f32_e32 v70, v173, v178
	v_exp_f32_e32 v70, v70
	s_nop 0
	v_add_f32_e32 v70, v70, v69
	v_cndmask_b32_e64 v69, v69, v70, s[40:41]
	ds_bpermute_b32 v70, v0, v186
	ds_bpermute_b32 v0, v0, v187
	s_waitcnt lgkmcnt(1)
	v_add_f32_e32 v70, v186, v70
	s_waitcnt lgkmcnt(0)
	v_add_f32_e32 v0, v187, v0
	ds_bpermute_b32 v71, v3, v70
	ds_bpermute_b32 v3, v3, v0
	s_waitcnt lgkmcnt(1)
	v_add_f32_e32 v70, v70, v71
	s_waitcnt lgkmcnt(0)
	v_add_f32_e32 v0, v0, v3
	v_add_f32_e32 v3, v173, v176
	v_exp_f32_e32 v3, v3
	v_add_f32_e32 v2, v2, v70
	v_cndmask_b32_e64 v2, v70, v2, s[40:41]
	v_add_f32_e32 v3, v3, v0
	v_cndmask_b32_e64 v0, v0, v3, s[40:41]
	v_div_scale_f32 v3, s[42:43], v2, v2, 1.0
	v_rcp_f32_e32 v70, v3
	s_nop 0
	v_fma_f32 v71, -v3, v70, 1.0
	v_fmac_f32_e32 v70, v71, v70
	v_div_scale_f32 v71, vcc, 1.0, v2, 1.0
	v_mul_f32_e32 v72, v71, v70
	v_fma_f32 v73, -v3, v72, v71
	v_fmac_f32_e32 v72, v73, v70
	v_fma_f32 v3, -v3, v72, v71
	v_div_fmas_f32 v3, v3, v70, v72
	v_div_fixup_f32 v71, v3, v2, 1.0
	v_div_scale_f32 v2, s[42:43], v69, v69, 1.0
	v_rcp_f32_e32 v3, v2
	s_nop 0
	v_fma_f32 v70, -v2, v3, 1.0
	v_fmac_f32_e32 v3, v70, v3
	v_div_scale_f32 v70, vcc, 1.0, v69, 1.0
	v_mul_f32_e32 v72, v70, v3
	v_fma_f32 v73, -v2, v72, v70
	v_fmac_f32_e32 v72, v73, v3
	v_fma_f32 v2, -v2, v72, v70
	v_div_fmas_f32 v2, v2, v3, v72
	v_div_fixup_f32 v72, v2, v69, 1.0
	v_div_scale_f32 v2, s[42:43], v68, v68, 1.0
	v_rcp_f32_e32 v3, v2
	s_nop 0
	v_fma_f32 v69, -v2, v3, 1.0
	v_fmac_f32_e32 v3, v69, v3
	v_div_scale_f32 v69, vcc, 1.0, v68, 1.0
	v_mul_f32_e32 v70, v69, v3
	v_fma_f32 v73, -v2, v70, v69
	v_fmac_f32_e32 v70, v73, v3
	v_fma_f32 v2, -v2, v70, v69
	v_div_fmas_f32 v2, v2, v3, v70
	v_div_fixup_f32 v73, v2, v68, 1.0
	v_div_scale_f32 v2, s[42:43], v0, v0, 1.0
	v_rcp_f32_e32 v3, v2
	s_lshl_b64 s[42:43], s[44:45], 1
	s_add_u32 s42, s68, s42
	s_addc_u32 s43, s69, s43
	v_fma_f32 v68, -v2, v3, 1.0
	v_fmac_f32_e32 v3, v68, v3
	v_div_scale_f32 v68, vcc, 1.0, v0, 1.0
	v_mul_f32_e32 v69, v68, v3
	v_fma_f32 v70, -v2, v69, v68
	v_fmac_f32_e32 v69, v70, v3
	v_fma_f32 v2, -v2, v69, v68
	v_div_fmas_f32 v2, v2, v3, v69
	v_div_fixup_f32 v70, v2, v0, 1.0
	v_add3_u32 v2, v175, s27, v179
	v_mov_b32_e32 v175, v1
	v_ashrrev_i32_e32 v3, 31, v2
	v_lshl_add_u64 v[68:69], s[42:43], 0, v[174:175]
	v_lshlrev_b64 v[74:75], 11, v[2:3]
	v_lshl_add_u64 v[2:3], v[68:69], 0, v[74:75]
	global_load_dwordx2 v[76:77], v[2:3], off
	global_load_dwordx2 v[78:79], v[2:3], off offset:32
	global_load_dwordx2 v[80:81], v[2:3], off offset:64
	global_load_dwordx2 v[82:83], v[2:3], off offset:96
	global_load_dwordx2 v[84:85], v[2:3], off offset:128
	global_load_dwordx2 v[86:87], v[2:3], off offset:160
	global_load_dwordx2 v[88:89], v[2:3], off offset:192
	global_load_dwordx2 v[90:91], v[2:3], off offset:224
	s_mov_b64 s[42:43], 0x8000
	v_lshl_add_u64 v[92:93], v[74:75], 0, s[42:43]
	v_lshl_add_u64 v[2:3], v[68:69], 0, v[92:93]
	global_load_dwordx2 v[94:95], v[2:3], off
	global_load_dwordx2 v[96:97], v[2:3], off offset:32
	global_load_dwordx2 v[98:99], v[2:3], off offset:64
	global_load_dwordx2 v[100:101], v[2:3], off offset:96
	global_load_dwordx2 v[102:103], v[2:3], off offset:128
	global_load_dwordx2 v[104:105], v[2:3], off offset:160
	global_load_dwordx2 v[68:69], v[2:3], off offset:192
	s_nop 0
	global_load_dwordx2 v[2:3], v[2:3], off offset:224
	v_mul_f32_e32 v52, v52, v73
	v_mul_f32_e32 v53, v53, v73
	v_lshl_add_u32 v0, v177, 2, s44
	s_mov_b64 s[42:43], 0
	s_waitcnt vmcnt(15)
	v_lshlrev_b32_e32 v106, 16, v76
	v_and_b32_e32 v76, 0xffff0000, v76
	v_mul_f32_e32 v52, v52, v106
	v_mul_f32_e32 v53, v53, v76
	v_cvt_pk_bf16_f32 v52, v52, v53
	v_mul_f32_e32 v53, v54, v73
	v_lshlrev_b32_e32 v54, 16, v77
	v_mul_f32_e32 v53, v53, v54
	v_mul_f32_e32 v54, v55, v73
	v_and_b32_e32 v55, 0xffff0000, v77
	v_mul_f32_e32 v54, v54, v55
	v_cvt_pk_bf16_f32 v53, v53, v54
	v_lshl_add_u64 v[54:55], s[16:17], 0, v[74:75]
	v_lshlrev_b64 v[74:75], 1, v[0:1]
	v_lshl_add_u64 v[54:55], v[54:55], 0, v[74:75]
	global_store_dwordx2 v[54:55], v[52:53], off sc1
	v_mul_f32_e32 v0, v60, v73
	s_waitcnt vmcnt(15)
	v_lshlrev_b32_e32 v52, 16, v78
	v_mul_f32_e32 v0, v0, v52
	v_mul_f32_e32 v52, v61, v73
	v_and_b32_e32 v53, 0xffff0000, v78
	v_mul_f32_e32 v52, v52, v53
	v_cvt_pk_bf16_f32 v52, v0, v52
	v_mul_f32_e32 v0, v62, v73
	v_lshlrev_b32_e32 v53, 16, v79
	v_mul_f32_e32 v0, v0, v53
	v_mul_f32_e32 v53, v63, v73
	v_and_b32_e32 v60, 0xffff0000, v79
	v_mul_f32_e32 v53, v53, v60
	v_cvt_pk_bf16_f32 v53, v0, v53
	global_store_dwordx2 v[54:55], v[52:53], off offset:32 sc1
	v_mul_f32_e32 v0, v56, v73
	s_waitcnt vmcnt(15)
; DI float bflo(unsigned w) { return __uint_as_float(w << 16); }
; DI float bfhi(unsigned w) { return __uint_as_float(w & 0xffff0000u); }
; template <int MODE> ...
;     ...
; #pragma unroll
;     for (int tt = 0; tt < 2; ++tt) {
;       const int row = yrow0 + w * 32 + tt * 16 + r;
; #pragma unroll
;       for (int hh = 0; hh < 2; ++hh)
; #pragma unroll
;         for (int dt = 0; dt < 4; ++dt) {
;           const int col = ycol0 + hh * 64 + dt * 16 + g * 4;
;           const float li = linv[tt][hh];
;           const uint2 gq = gg[tt][hh][dt];
;           uint2 o;
;           o.x = pack2(O[tt][hh][dt][0] * li * bflo(gq.x), O[tt][hh][dt][1] * li * bfhi(gq.x));
;           o.y = pack2(O[tt][hh][dt][2] * li * bflo(gq.y), O[tt][hh][dt][3] * li * bfhi(gq.y));
;           *(uint2*)(p.H + (size_t)row * 1024 + col) = o;
;         }
	v_lshlrev_b32_e32 v52, 16, v80
	v_mul_f32_e32 v0, v0, v52
	v_mul_f32_e32 v52, v57, v73
	v_and_b32_e32 v53, 0xffff0000, v80
	v_mul_f32_e32 v52, v52, v53
	v_cvt_pk_bf16_f32 v52, v0, v52
	v_mul_f32_e32 v0, v58, v73
	v_lshlrev_b32_e32 v53, 16, v81
	v_mul_f32_e32 v0, v0, v53
	v_mul_f32_e32 v53, v59, v73
	v_and_b32_e32 v56, 0xffff0000, v81
	v_mul_f32_e32 v53, v53, v56
	v_cvt_pk_bf16_f32 v53, v0, v53
	global_store_dwordx2 v[54:55], v[52:53], off offset:64 sc1
	v_mul_f32_e32 v0, v64, v73
	s_waitcnt vmcnt(15)
	v_lshlrev_b32_e32 v52, 16, v82
	v_mul_f32_e32 v0, v0, v52
	v_mul_f32_e32 v52, v65, v73
	v_and_b32_e32 v53, 0xffff0000, v82
	v_mul_f32_e32 v52, v52, v53
	v_cvt_pk_bf16_f32 v52, v0, v52
	v_mul_f32_e32 v0, v66, v73
	v_lshlrev_b32_e32 v53, 16, v83
	v_mul_f32_e32 v0, v0, v53
	v_mul_f32_e32 v53, v67, v73
	v_and_b32_e32 v56, 0xffff0000, v83
	v_mul_f32_e32 v53, v53, v56
	v_cvt_pk_bf16_f32 v53, v0, v53
	v_mul_f32_e32 v0, v44, v72
	s_waitcnt vmcnt(14)
	v_lshlrev_b32_e32 v44, 16, v84
	v_mul_f32_e32 v0, v0, v44
	v_mul_f32_e32 v44, v45, v72
	v_and_b32_e32 v45, 0xffff0000, v84
	v_mul_f32_e32 v44, v44, v45
	v_cvt_pk_bf16_f32 v44, v0, v44
	v_mul_f32_e32 v0, v46, v72
	v_lshlrev_b32_e32 v45, 16, v85
	v_mul_f32_e32 v0, v0, v45
	v_mul_f32_e32 v45, v47, v72
	v_and_b32_e32 v46, 0xffff0000, v85
	v_mul_f32_e32 v45, v45, v46
	v_cvt_pk_bf16_f32 v45, v0, v45
	v_mul_f32_e32 v0, v40, v72
	s_waitcnt vmcnt(13)
	v_lshlrev_b32_e32 v40, 16, v86
	v_mul_f32_e32 v0, v0, v40
	v_mul_f32_e32 v40, v41, v72
	v_and_b32_e32 v41, 0xffff0000, v86
	v_mul_f32_e32 v40, v40, v41
	v_cvt_pk_bf16_f32 v40, v0, v40
	v_mul_f32_e32 v0, v42, v72
	v_lshlrev_b32_e32 v41, 16, v87
	v_mul_f32_e32 v0, v0, v41
	v_mul_f32_e32 v41, v43, v72
	v_and_b32_e32 v42, 0xffff0000, v87
	v_mul_f32_e32 v41, v41, v42
	v_cvt_pk_bf16_f32 v41, v0, v41
	v_mul_f32_e32 v0, v36, v72
	s_waitcnt vmcnt(12)
	v_lshlrev_b32_e32 v36, 16, v88
	v_mul_f32_e32 v0, v0, v36
	v_mul_f32_e32 v36, v37, v72
	v_and_b32_e32 v37, 0xffff0000, v88
	v_mul_f32_e32 v36, v36, v37
	v_cvt_pk_bf16_f32 v36, v0, v36
	v_mul_f32_e32 v0, v38, v72
	v_lshlrev_b32_e32 v37, 16, v89
	v_mul_f32_e32 v0, v0, v37
	v_mul_f32_e32 v37, v39, v72
	v_and_b32_e32 v38, 0xffff0000, v89
	v_mul_f32_e32 v37, v37, v38
	v_cvt_pk_bf16_f32 v37, v0, v37
	global_store_dwordx2 v[54:55], v[36:37], off offset:192 sc1
	v_mul_f32_e32 v0, v48, v72
	s_waitcnt vmcnt(12)
	v_lshlrev_b32_e32 v36, 16, v90
	v_mul_f32_e32 v0, v0, v36
	v_mul_f32_e32 v36, v49, v72
	v_and_b32_e32 v37, 0xffff0000, v90
	v_mul_f32_e32 v36, v36, v37
	v_cvt_pk_bf16_f32 v36, v0, v36
	v_mul_f32_e32 v0, v50, v72
	v_lshlrev_b32_e32 v37, 16, v91
	v_mul_f32_e32 v0, v0, v37
	v_mul_f32_e32 v37, v51, v72
	v_and_b32_e32 v38, 0xffff0000, v91
	v_mul_f32_e32 v37, v37, v38
	v_cvt_pk_bf16_f32 v37, v0, v37
	v_mul_f32_e32 v0, v32, v71
	s_waitcnt vmcnt(11)
	v_lshlrev_b32_e32 v32, 16, v94
	v_mul_f32_e32 v0, v0, v32
	v_mul_f32_e32 v32, v33, v71
	v_and_b32_e32 v33, 0xffff0000, v94
	v_mul_f32_e32 v32, v32, v33
	v_cvt_pk_bf16_f32 v32, v0, v32
	v_mul_f32_e32 v0, v34, v71
	v_lshlrev_b32_e32 v33, 16, v95
	v_mul_f32_e32 v0, v0, v33
	v_mul_f32_e32 v33, v35, v71
	v_and_b32_e32 v34, 0xffff0000, v95
	v_mul_f32_e32 v33, v33, v34
	v_cvt_pk_bf16_f32 v33, v0, v33
	v_mul_f32_e32 v0, v28, v71
	s_waitcnt vmcnt(10)
	v_lshlrev_b32_e32 v28, 16, v96
	v_mul_f32_e32 v0, v0, v28
	v_mul_f32_e32 v28, v29, v71
	v_and_b32_e32 v29, 0xffff0000, v96
	v_mul_f32_e32 v28, v28, v29
	v_cvt_pk_bf16_f32 v28, v0, v28
	v_mul_f32_e32 v0, v30, v71
	v_lshlrev_b32_e32 v29, 16, v97
	v_mul_f32_e32 v0, v0, v29
	v_mul_f32_e32 v29, v31, v71
	v_and_b32_e32 v30, 0xffff0000, v97
	v_mul_f32_e32 v29, v29, v30
	v_cvt_pk_bf16_f32 v29, v0, v29
	v_mul_f32_e32 v0, v24, v71
	s_waitcnt vmcnt(9)
; DI float bflo(unsigned w) { return __uint_as_float(w << 16); }
; DI float bfhi(unsigned w) { return __uint_as_float(w & 0xffff0000u); }
; template <int MODE> ...
;     ...
; #pragma unroll
;     for (int tt = 0; tt < 2; ++tt) {
;       const int row = yrow0 + w * 32 + tt * 16 + r;
; #pragma unroll
;       for (int hh = 0; hh < 2; ++hh)
; #pragma unroll
;         for (int dt = 0; dt < 4; ++dt) {
;           const int col = ycol0 + hh * 64 + dt * 16 + g * 4;
;           const float li = linv[tt][hh];
;           const uint2 gq = gg[tt][hh][dt];
;           uint2 o;
;           o.x = pack2(O[tt][hh][dt][0] * li * bflo(gq.x), O[tt][hh][dt][1] * li * bfhi(gq.x));
;           o.y = pack2(O[tt][hh][dt][2] * li * bflo(gq.y), O[tt][hh][dt][3] * li * bfhi(gq.y));
;           *(uint2*)(p.H + (size_t)row * 1024 + col) = o;
;         }
	v_lshlrev_b32_e32 v24, 16, v98
	v_mul_f32_e32 v0, v0, v24
	v_mul_f32_e32 v24, v25, v71
	v_and_b32_e32 v25, 0xffff0000, v98
	v_mul_f32_e32 v24, v24, v25
	v_cvt_pk_bf16_f32 v24, v0, v24
	v_mul_f32_e32 v0, v26, v71
	v_lshlrev_b32_e32 v25, 16, v99
	v_mul_f32_e32 v0, v0, v25
	v_mul_f32_e32 v25, v27, v71
	v_and_b32_e32 v26, 0xffff0000, v99
	v_mul_f32_e32 v25, v25, v26
	v_cvt_pk_bf16_f32 v25, v0, v25
	v_mul_f32_e32 v0, v20, v71
	s_waitcnt vmcnt(8)
	v_lshlrev_b32_e32 v20, 16, v100
	v_mul_f32_e32 v0, v0, v20
	v_mul_f32_e32 v20, v21, v71
	v_and_b32_e32 v21, 0xffff0000, v100
	v_mul_f32_e32 v20, v20, v21
	v_cvt_pk_bf16_f32 v20, v0, v20
	v_mul_f32_e32 v0, v22, v71
	v_lshlrev_b32_e32 v21, 16, v101
	v_mul_f32_e32 v0, v0, v21
	v_mul_f32_e32 v21, v23, v71
	v_and_b32_e32 v22, 0xffff0000, v101
	v_mul_f32_e32 v21, v21, v22
	v_cvt_pk_bf16_f32 v21, v0, v21
	v_mul_f32_e32 v0, v16, v70
	s_waitcnt vmcnt(7)
	v_lshlrev_b32_e32 v16, 16, v102
	v_mul_f32_e32 v0, v0, v16
	v_mul_f32_e32 v16, v17, v70
	v_and_b32_e32 v17, 0xffff0000, v102
	v_mul_f32_e32 v16, v16, v17
	v_cvt_pk_bf16_f32 v16, v0, v16
	v_mul_f32_e32 v0, v18, v70
	v_lshlrev_b32_e32 v17, 16, v103
	v_mul_f32_e32 v0, v0, v17
	v_mul_f32_e32 v17, v19, v70
	v_and_b32_e32 v18, 0xffff0000, v103
	v_mul_f32_e32 v17, v17, v18
	v_cvt_pk_bf16_f32 v17, v0, v17
	v_mul_f32_e32 v0, v12, v70
	s_waitcnt vmcnt(6)
	v_lshlrev_b32_e32 v12, 16, v104
	v_mul_f32_e32 v0, v0, v12
	v_mul_f32_e32 v12, v13, v70
	v_and_b32_e32 v13, 0xffff0000, v104
	v_mul_f32_e32 v12, v12, v13
	v_cvt_pk_bf16_f32 v12, v0, v12
	v_mul_f32_e32 v0, v14, v70
	v_lshlrev_b32_e32 v13, 16, v105
	v_mul_f32_e32 v0, v0, v13
	v_mul_f32_e32 v13, v15, v70
	v_and_b32_e32 v14, 0xffff0000, v105
	v_mul_f32_e32 v13, v13, v14
	v_cvt_pk_bf16_f32 v13, v0, v13
	v_mul_f32_e32 v0, v8, v70
	s_waitcnt vmcnt(5)
	v_lshlrev_b32_e32 v8, 16, v68
	v_mul_f32_e32 v0, v0, v8
	v_mul_f32_e32 v8, v9, v70
	v_and_b32_e32 v9, 0xffff0000, v68
	v_mul_f32_e32 v8, v8, v9
	v_cvt_pk_bf16_f32 v8, v0, v8
	v_mul_f32_e32 v0, v10, v70
	v_lshlrev_b32_e32 v9, 16, v69
	v_mul_f32_e32 v0, v0, v9
	v_mul_f32_e32 v9, v11, v70
	v_and_b32_e32 v10, 0xffff0000, v69
	v_mul_f32_e32 v9, v9, v10
	v_cvt_pk_bf16_f32 v9, v0, v9
	v_mul_f32_e32 v0, v4, v70
	s_waitcnt vmcnt(4)
	v_lshlrev_b32_e32 v4, 16, v2
	v_mul_f32_e32 v0, v0, v4
	v_mul_f32_e32 v4, v5, v70
	v_and_b32_e32 v2, 0xffff0000, v2
	v_mul_f32_e32 v2, v4, v2
	v_cvt_pk_bf16_f32 v2, v0, v2
	v_mul_f32_e32 v0, v6, v70
	v_lshlrev_b32_e32 v4, 16, v3
	v_mul_f32_e32 v0, v0, v4
	v_mul_f32_e32 v4, v7, v70
	v_and_b32_e32 v3, 0xffff0000, v3
	v_lshl_add_u64 v[34:35], s[16:17], 0, v[92:93]
	v_mul_f32_e32 v3, v4, v3
	v_lshl_add_u64 v[34:35], v[34:35], 0, v[74:75]
	v_cvt_pk_bf16_f32 v3, v0, v3
	global_store_dwordx2 v[54:55], v[52:53], off offset:96 sc1
	global_store_dwordx2 v[54:55], v[44:45], off offset:128 sc1
	global_store_dwordx2 v[54:55], v[40:41], off offset:160 sc1
	global_store_dwordx2 v[54:55], v[36:37], off offset:224 sc1
	global_store_dwordx2 v[34:35], v[32:33], off sc1
	global_store_dwordx2 v[34:35], v[28:29], off offset:32 sc1
	global_store_dwordx2 v[34:35], v[24:25], off offset:64 sc1
	global_store_dwordx2 v[34:35], v[20:21], off offset:96 sc1
	global_store_dwordx2 v[34:35], v[16:17], off offset:128 sc1
	global_store_dwordx2 v[34:35], v[12:13], off offset:160 sc1
	global_store_dwordx2 v[34:35], v[8:9], off offset:192 sc1
	global_store_dwordx2 v[34:35], v[2:3], off offset:224 sc1

; template <int MODE> ...
;     ...
;   float linv[2][2];
; #pragma unroll
;   for (int tt = 0; tt < 2; ++tt)
; #pragma unroll
;     for (int hh = 0; hh < 2; ++hh) {
;       float lt = lsum[tt][hh];
;       lt += __shfl_xor(lt, 16);
;       lt += __shfl_xor(lt, 32);
;       if (has_sink) lt += __builtin_amdgcn_exp2f((hh ? sink1 : sink0) + nbias[tt][hh]);
;       linv[tt][hh] = 1.f / lt;
;     ...
;     uint2 gg[2][4];
;     float4 sgv[4];
; #pragma unroll
;     for (int dt = 0; dt < 4; ++dt) sgv[dt] = *(const float4*)(subln + dt * 16 + g * 4);
; #pragma unroll
;     for (int tt = 0; tt < 2; ++tt)
; #pragma unroll
;       for (int dt = 0; dt < 4; ++dt)
;         gg[tt][dt] = *(const uint2*)(p.G + (size_t)(yrow0 + w * 32 + tt * 16 + r) * 1024 + ycol0 + dt * 16 + g * 4);
; #pragma unroll
;     for (int tt = 0; tt < 2; ++tt) {
;       const int row = yrow0 + w * 32 + tt * 16 + r;
;       float ov[4][4];
;       float ss = 0.f;
; #pragma unroll
;       for (int dt = 0; dt < 4; ++dt)
; #pragma unroll
;         for (int j = 0; j < 4; ++j) {
;           const float v = O[tt][0][dt][j] * linv[tt][0] - lam * O[tt][1][dt][j] * linv[tt][1];
;           ov[dt][j] = v;
;           ss += v * v;
;         }
;       ss += __shfl_xor(ss, 16);
;       ss += __shfl_xor(ss, 32);
.LBB0_897:
	v_and_b32_e32 v19, 64, v226
	v_xor_b32_e32 v18, 16, v226
	v_add_u32_e32 v19, 64, v19
	v_cmp_lt_i32_e32 vcc, v18, v19
	v_readlane_b32 s42, v255, 54
	v_readlane_b32 s43, v255, 55
	v_cndmask_b32_e32 v18, v226, v18, vcc
	v_lshlrev_b32_e32 v118, 2, v18
	v_xor_b32_e32 v18, 32, v226
	s_waitcnt vmcnt(1)
	ds_bpermute_b32 v50, v118, v170
	ds_bpermute_b32 v51, v118, v171
	v_cmp_lt_i32_e32 vcc, v18, v19
	s_mov_b32 s45, s3
	v_readlane_b32 s48, v255, 28
	v_cndmask_b32_e32 v18, v226, v18, vcc
	v_lshlrev_b32_e32 v119, 2, v18
	v_add_f32_e32 v18, v172, v162
	v_exp_f32_e32 v98, v18
	v_add_f32_e32 v18, v173, v164
	v_exp_f32_e32 v99, v18
	v_add_f32_e32 v18, v172, v160
	s_waitcnt lgkmcnt(0)
	v_pk_add_f32 v[110:111], v[170:171], v[50:51]
	v_exp_f32_e32 v102, v18
	v_add_f32_e32 v18, v173, v158
	ds_bpermute_b32 v112, v119, v110
	ds_bpermute_b32 v113, v119, v111
	v_exp_f32_e32 v103, v18
	global_load_dwordx4 v[30:33], v0, s[42:43]
	global_load_dwordx4 v[26:29], v0, s[42:43] offset:64
	global_load_dwordx4 v[22:25], v0, s[42:43] offset:128
	global_load_dwordx4 v[18:21], v0, s[42:43] offset:192
	s_lshl_b64 s[42:43], s[44:45], 1
	v_add3_u32 v52, v155, s27, v161
	v_readlane_b32 s49, v255, 29
	s_add_u32 s42, s48, s42
	s_addc_u32 s43, s49, s43
	v_mov_b32_e32 v155, v1
	v_ashrrev_i32_e32 v53, 31, v52
	s_waitcnt vmcnt(4)
	v_lshl_add_u64 v[54:55], s[42:43], 0, v[154:155]
	v_lshlrev_b64 v[104:105], 11, v[52:53]
	s_mov_b64 s[42:43], 0x8000
	v_lshl_add_u64 v[56:57], v[104:105], 0, s[42:43]
	s_waitcnt lgkmcnt(0)
	v_pk_add_f32 v[110:111], v[110:111], v[112:113]
	v_lshl_add_u64 v[52:53], v[54:55], 0, v[104:105]
	v_lshl_add_u64 v[108:109], v[54:55], 0, v[56:57]
	v_pk_add_f32 v[98:99], v[98:99], v[110:111]
	global_load_dwordx2 v[106:107], v[52:53], off
	global_load_dwordx2 v[96:97], v[52:53], off offset:32
	global_load_dwordx2 v[94:95], v[52:53], off offset:64
	global_load_dwordx2 v[92:93], v[52:53], off offset:96
	global_load_dwordx2 v[90:91], v[108:109], off
	global_load_dwordx2 v[54:55], v[108:109], off offset:32
	s_nop 0
	global_load_dwordx2 v[52:53], v[108:109], off offset:64
	global_load_dwordx2 v[50:51], v[108:109], off offset:96
	v_mul_f32_e32 v109, v228, v86
	v_cndmask_b32_e64 v86, v111, v99, s[40:41]
	v_div_scale_f32 v108, s[42:43], v86, v86, 1.0
	v_rcp_f32_e32 v111, v108
	v_mul_f32_e32 v99, v228, v88
	v_cndmask_b32_e64 v88, v110, v98, s[40:41]
	v_mul_f32_e32 v67, v228, v67
	v_fma_f32 v98, -v108, v111, 1.0
	v_fmac_f32_e32 v111, v98, v111
	v_div_scale_f32 v98, vcc, 1.0, v86, 1.0
	v_mul_f32_e32 v110, v98, v111
	v_fma_f32 v112, -v108, v110, v98
	v_fmac_f32_e32 v110, v112, v111
	v_fma_f32 v98, -v108, v110, v98
	v_div_scale_f32 v108, s[42:43], v88, v88, 1.0
	v_rcp_f32_e32 v112, v108
	v_div_fmas_f32 v98, v98, v111, v110
	v_div_fixup_f32 v111, v98, v86, 1.0
	v_mul_f32_e32 v87, v228, v87
	v_fma_f32 v86, -v108, v112, 1.0
	v_fmac_f32_e32 v112, v86, v112
	v_div_scale_f32 v86, vcc, 1.0, v88, 1.0
	v_mul_f32_e32 v98, v86, v112
	v_fma_f32 v110, -v108, v98, v86
	v_fmac_f32_e32 v98, v110, v112
	v_fma_f32 v86, -v108, v98, v86
	v_div_fmas_f32 v86, v86, v112, v98
	v_div_fixup_f32 v110, v86, v88, 1.0
	v_mov_b32_e32 v86, v71
	v_mul_f32_e32 v71, v228, v66
	v_mov_b32_e32 v66, v79
	v_pk_mul_f32 v[116:117], v[66:67], v[110:111]
	v_mul_f32_e32 v67, v228, v68
	v_mov_b32_e32 v66, v80
	ds_bpermute_b32 v100, v118, v156
	ds_bpermute_b32 v101, v118, v157
	v_pk_mul_f32 v[112:113], v[86:87], v[110:111]
	v_pk_mul_f32 v[86:87], v[66:67], v[110:111]
	v_mul_f32_e32 v67, v228, v69
	v_mov_b32_e32 v66, v81
	v_mov_b32_e32 v108, v70
	v_mov_b32_e32 v70, v78
	v_pk_mul_f32 v[78:79], v[66:67], v[110:111]
	v_mul_f32_e32 v67, v228, v58
	v_mov_b32_e32 v66, v62
	v_mul_f32_e32 v59, v228, v59
	v_mov_b32_e32 v58, v63
	v_pk_mul_f32 v[66:67], v[66:67], v[110:111]
	v_pk_mul_f32 v[58:59], v[58:59], v[110:111]
	v_mov_b32_e32 v63, v66
	v_mov_b32_e32 v62, v58
	v_mov_b32_e32 v66, v59
	v_mul_f32_e32 v59, v228, v60
	v_mov_b32_e32 v58, v64
	v_mul_f32_e32 v61, v228, v61
	v_mov_b32_e32 v60, v65
	v_pk_mul_f32 v[58:59], v[58:59], v[110:111]
	v_pk_mul_f32 v[60:61], v[60:61], v[110:111]
	v_mov_b32_e32 v65, v58
	v_mov_b32_e32 v64, v60
	v_mov_b32_e32 v58, v61
	s_waitcnt lgkmcnt(0)
	v_pk_add_f32 v[80:81], v[156:157], v[100:101]
	v_pk_add_f32 v[60:61], v[64:65], v[58:59] neg_lo:[0,1] neg_hi:[0,1]
	v_mul_f32_e32 v59, v228, v82
	v_mul_f32_e32 v65, v228, v83
	ds_bpermute_b32 v82, v119, v80
	ds_bpermute_b32 v83, v119, v81
	v_mov_b32_e32 v58, v74
	v_mov_b32_e32 v64, v75
	v_pk_mul_f32 v[58:59], v[58:59], v[110:111]
	v_pk_mul_f32 v[64:65], v[64:65], v[110:111]
	s_waitcnt lgkmcnt(0)
; template <int MODE> ...
;     ...
; #pragma unroll
;     for (int tt = 0; tt < 2; ++tt) {
;       const int row = yrow0 + w * 32 + tt * 16 + r;
;       float ov[4][4];
;       float ss = 0.f;
; #pragma unroll
;       for (int dt = 0; dt < 4; ++dt)
; #pragma unroll
;         for (int j = 0; j < 4; ++j) {
;           const float v = O[tt][0][dt][j] * linv[tt][0] - lam * O[tt][1][dt][j] * linv[tt][1];
;           ov[dt][j] = v;
;           ss += v * v;
;         }
;       ss += __shfl_xor(ss, 16);
;       ss += __shfl_xor(ss, 32);
	v_pk_add_f32 v[80:81], v[80:81], v[82:83]
	v_pk_add_f32 v[62:63], v[62:63], v[66:67] neg_lo:[0,1] neg_hi:[0,1]
	v_mov_b32_e32 v66, v64
	v_mov_b32_e32 v67, v58
	v_mov_b32_e32 v58, v65
	v_pk_add_f32 v[82:83], v[102:103], v[80:81]
	v_pk_add_f32 v[64:65], v[66:67], v[58:59] neg_lo:[0,1] neg_hi:[0,1]
	v_mul_f32_e32 v67, v228, v85
	v_mul_f32_e32 v85, v228, v46
	v_cndmask_b32_e64 v46, v81, v83, s[40:41]
	v_div_scale_f32 v83, s[42:43], v46, v46, 1.0
	v_mul_f32_e32 v59, v228, v84
	v_rcp_f32_e32 v84, v83
	v_mul_f32_e32 v81, v228, v48
	v_cndmask_b32_e64 v48, v80, v82, s[40:41]
	v_mul_f32_e32 v49, v228, v49
	v_fma_f32 v80, -v83, v84, 1.0
	v_fmac_f32_e32 v84, v80, v84
	v_div_scale_f32 v80, vcc, 1.0, v46, 1.0
	v_mul_f32_e32 v82, v80, v84
	v_fma_f32 v100, -v83, v82, v80
	v_fmac_f32_e32 v82, v100, v84
	v_div_scale_f32 v100, s[40:41], v48, v48, 1.0
	v_rcp_f32_e32 v101, v100
	v_fma_f32 v80, -v83, v82, v80
	v_div_fmas_f32 v80, v80, v84, v82
	v_div_fixup_f32 v83, v80, v46, 1.0
	v_fma_f32 v46, -v100, v101, 1.0
	v_fmac_f32_e32 v101, v46, v101
	v_div_scale_f32 v46, vcc, 1.0, v48, 1.0
	v_mul_f32_e32 v80, v46, v101
	v_fma_f32 v82, -v100, v80, v46
	v_fmac_f32_e32 v80, v82, v101
	v_fma_f32 v46, -v100, v80, v46
	v_div_fmas_f32 v46, v46, v101, v80
	v_div_fixup_f32 v82, v46, v48, 1.0
	v_mov_b32_e32 v48, v45
	v_mov_b32_e32 v80, v44
	v_pk_mul_f32 v[44:45], v[48:49], v[82:83]
	v_mul_f32_e32 v49, v228, v38
	v_mul_f32_e32 v39, v228, v39
	v_mov_b32_e32 v38, v35
	v_mov_b32_e32 v48, v34
	v_pk_mul_f32 v[34:35], v[38:39], v[82:83]
	v_mul_f32_e32 v39, v228, v40
	v_mul_f32_e32 v41, v228, v41
	v_mov_b32_e32 v40, v37
	v_mul_f32_e32 v47, v228, v47
	v_mov_b32_e32 v46, v43
	v_mov_b32_e32 v38, v36
	v_pk_mul_f32 v[36:37], v[40:41], v[82:83]
	v_mul_f32_e32 v41, v228, v14
	v_mov_b32_e32 v40, v10
	v_mul_f32_e32 v15, v228, v15
	v_mov_b32_e32 v14, v11
	v_mov_b32_e32 v84, v42
	v_pk_mul_f32 v[42:43], v[46:47], v[82:83]
	v_pk_mul_f32 v[40:41], v[40:41], v[82:83]
	v_pk_mul_f32 v[10:11], v[14:15], v[82:83]
	v_pk_mul_f32 v[108:109], v[108:109], v[110:111]
	v_mov_b32_e32 v98, v72
	v_pk_mul_f32 v[84:85], v[84:85], v[82:83]
	v_pk_mul_f32 v[46:47], v[80:81], v[82:83]
	v_mov_b32_e32 v14, v10
	v_mov_b32_e32 v15, v40
	v_mov_b32_e32 v40, v11
	v_mov_b32_e32 v80, v42
	v_mov_b32_e32 v81, v112
	v_mov_b32_e32 v112, v43
	v_mul_f32_e32 v89, v228, v89
	v_pk_mul_f32 v[98:99], v[98:99], v[110:111]
	v_mov_b32_e32 v88, v73
	v_pk_add_f32 v[10:11], v[14:15], v[40:41] neg_lo:[0,1] neg_hi:[0,1]
	v_mov_b32_e32 v40, v84
	v_mov_b32_e32 v41, v108
	v_mov_b32_e32 v108, v85
	v_pk_add_f32 v[42:43], v[80:81], v[112:113] neg_lo:[0,1] neg_hi:[0,1]
	v_pk_mul_f32 v[88:89], v[88:89], v[110:111]
	v_pk_add_f32 v[40:41], v[40:41], v[108:109] neg_lo:[0,1] neg_hi:[0,1]
	v_pk_mul_f32 v[80:81], v[42:43], v[42:43]
	v_mov_b32_e32 v84, v46
	v_mov_b32_e32 v85, v98
	v_mov_b32_e32 v98, v47
	v_pk_mul_f32 v[114:115], v[70:71], v[110:111]
	v_pk_mul_f32 v[48:49], v[48:49], v[82:83]
	v_pk_fma_f32 v[80:81], v[40:41], v[40:41], v[80:81]
	v_pk_add_f32 v[46:47], v[84:85], v[98:99] neg_lo:[0,1] neg_hi:[0,1]
	v_mov_b32_e32 v84, v44
	v_mov_b32_e32 v85, v88
	v_mov_b32_e32 v88, v45
	v_pk_fma_f32 v[80:81], v[46:47], v[46:47], v[80:81]
	v_pk_add_f32 v[44:45], v[84:85], v[88:89] neg_lo:[0,1] neg_hi:[0,1]
	v_mov_b32_e32 v84, v48
	v_mov_b32_e32 v85, v114
	v_mov_b32_e32 v114, v49
	v_pk_mul_f32 v[38:39], v[38:39], v[82:83]
	v_pk_fma_f32 v[80:81], v[44:45], v[44:45], v[80:81]
	v_pk_add_f32 v[48:49], v[84:85], v[114:115] neg_lo:[0,1] neg_hi:[0,1]
	v_mov_b32_e32 v84, v34
	v_mov_b32_e32 v85, v116
	v_mov_b32_e32 v116, v35
	v_pk_fma_f32 v[80:81], v[48:49], v[48:49], v[80:81]
	v_pk_add_f32 v[34:35], v[84:85], v[116:117] neg_lo:[0,1] neg_hi:[0,1]
	v_mov_b32_e32 v84, v38
	v_mov_b32_e32 v85, v86
	v_mov_b32_e32 v86, v39
	v_pk_fma_f32 v[80:81], v[34:35], v[34:35], v[80:81]
	v_pk_add_f32 v[38:39], v[84:85], v[86:87] neg_lo:[0,1] neg_hi:[0,1]
	v_mov_b32_e32 v84, v36
	v_mov_b32_e32 v85, v78
	v_mov_b32_e32 v78, v37
	v_pk_mul_f32 v[70:71], v[62:63], v[62:63]
	v_pk_mul_f32 v[14:15], v[10:11], v[10:11]
	v_pk_fma_f32 v[80:81], v[38:39], v[38:39], v[80:81]
	v_pk_add_f32 v[36:37], v[84:85], v[78:79] neg_lo:[0,1] neg_hi:[0,1]
	v_mul_f32_e32 v17, v228, v17
	v_pk_fma_f32 v[78:79], v[36:37], v[36:37], v[80:81]
	v_mov_b32_e32 v80, v15
	v_mov_b32_e32 v81, v71
	v_pk_add_f32 v[78:79], v[80:81], v[78:79]
	v_mul_f32_e32 v81, v228, v16
	v_mov_b32_e32 v80, v12
	v_mov_b32_e32 v16, v13
	v_pk_mul_f32 v[80:81], v[80:81], v[82:83]
	v_pk_mul_f32 v[12:13], v[16:17], v[82:83]
	v_mov_b32_e32 v17, v80
	v_mov_b32_e32 v16, v12
	v_mov_b32_e32 v80, v13
	v_pk_add_f32 v[12:13], v[16:17], v[80:81] neg_lo:[0,1] neg_hi:[0,1]
	v_mul_f32_e32 v81, v228, v2
	v_mov_b32_e32 v80, v6
	v_mul_f32_e32 v3, v228, v3
	v_mov_b32_e32 v2, v7
	v_pk_mul_f32 v[80:81], v[80:81], v[82:83]
	v_pk_mul_f32 v[2:3], v[2:3], v[82:83]
	v_mov_b32_e32 v7, v80
	v_mov_b32_e32 v6, v2
	v_mov_b32_e32 v80, v3
	v_pk_mul_f32 v[72:73], v[60:61], v[60:61]
	v_mov_b32_e32 v58, v76
	v_mov_b32_e32 v66, v77
	v_pk_mul_f32 v[16:17], v[12:13], v[12:13]
	v_pk_add_f32 v[2:3], v[6:7], v[80:81] neg_lo:[0,1] neg_hi:[0,1]
	v_mul_f32_e32 v81, v228, v4
	v_mov_b32_e32 v80, v8
	v_mul_f32_e32 v5, v228, v5
	v_mov_b32_e32 v4, v9
	v_mov_b32_e32 v15, v70
	v_pk_mul_f32 v[58:59], v[58:59], v[110:111]
	v_pk_mul_f32 v[66:67], v[66:67], v[110:111]
	v_pk_mul_f32 v[80:81], v[80:81], v[82:83]
	v_pk_mul_f32 v[4:5], v[4:5], v[82:83]
	v_pk_add_f32 v[14:15], v[14:15], v[78:79]
	v_mov_b32_e32 v70, v17
	v_mov_b32_e32 v71, v73
	v_pk_mul_f32 v[74:75], v[64:65], v[64:65]
	v_mov_b32_e32 v68, v66
	v_mov_b32_e32 v69, v58
	v_mov_b32_e32 v58, v67
	v_pk_mul_f32 v[6:7], v[2:3], v[2:3]
	v_mov_b32_e32 v8, v4
	v_mov_b32_e32 v9, v80
	v_mov_b32_e32 v80, v5
	v_pk_add_f32 v[14:15], v[70:71], v[14:15]
	v_mov_b32_e32 v17, v72
	v_pk_add_f32 v[66:67], v[68:69], v[58:59] neg_lo:[0,1] neg_hi:[0,1]
	v_pk_add_f32 v[4:5], v[8:9], v[80:81] neg_lo:[0,1] neg_hi:[0,1]
	v_pk_add_f32 v[14:15], v[16:17], v[14:15]
	v_mov_b32_e32 v16, v7
	v_mov_b32_e32 v17, v75
	v_pk_mul_f32 v[76:77], v[66:67], v[66:67]
	v_pk_mul_f32 v[8:9], v[4:5], v[4:5]
	v_pk_add_f32 v[14:15], v[16:17], v[14:15]
	v_mov_b32_e32 v7, v74
	v_pk_add_f32 v[6:7], v[6:7], v[14:15]
	v_mov_b32_e32 v14, v9
	v_mov_b32_e32 v15, v77
	v_pk_add_f32 v[6:7], v[14:15], v[6:7]
	v_mov_b32_e32 v9, v76
	v_pk_add_f32 v[6:7], v[8:9], v[6:7]
	ds_bpermute_b32 v9, v118, v7
	ds_bpermute_b32 v8, v118, v6
	s_waitcnt vmcnt(7)
; DI float bflo(unsigned w) { return __uint_as_float(w << 16); }
; DI float bfhi(unsigned w) { return __uint_as_float(w & 0xffff0000u); }
; template <int MODE> ...
;     ...
; #pragma unroll
;     for (int tt = 0; tt < 2; ++tt) {
;       const int row = yrow0 + w * 32 + tt * 16 + r;
;       float ov[4][4];
;       float ss = 0.f;
; #pragma unroll
;       for (int dt = 0; dt < 4; ++dt)
; #pragma unroll
;         for (int j = 0; j < 4; ++j) {
;           const float v = O[tt][0][dt][j] * linv[tt][0] - lam * O[tt][1][dt][j] * linv[tt][1];
;           ov[dt][j] = v;
;           ss += v * v;
;         }
;       ss += __shfl_xor(ss, 16);
;       ss += __shfl_xor(ss, 32);
;       const float rinv = rsqrtf(ss * (1.f / 64.f) + 1e-6f) * outscale;
; #pragma unroll
;       for (int dt = 0; dt < 4; ++dt) {
;         const int col = ycol0 + dt * 16 + g * 4;
;         const uint2 gq = gg[tt][dt];
;         const float4 sg = sgv[dt];
;         uint2 o;
;         o.x = pack2(ov[dt][0] * rinv * sg.x * bflo(gq.x), ov[dt][1] * rinv * sg.y * bfhi(gq.x));
;         o.y = pack2(ov[dt][2] * rinv * sg.z * bflo(gq.y), ov[dt][3] * rinv * sg.w * bfhi(gq.y));
;         *(uint2*)(p.H + (size_t)row * 1024 + col) = o;
;       }
	v_lshlrev_b32_e32 v110, 16, v106
	v_and_b32_e32 v106, 0xffff0000, v106
	v_lshl_add_u32 v0, v159, 2, s44
	v_lshlrev_b32_e32 v111, 16, v107
	s_waitcnt lgkmcnt(0)
	v_pk_add_f32 v[6:7], v[6:7], v[8:9]
	ds_bpermute_b32 v9, v119, v7
	ds_bpermute_b32 v8, v119, v6
	v_and_b32_e32 v107, 0xffff0000, v107
	v_lshl_add_u64 v[68:69], s[16:17], 0, v[104:105]
	v_lshlrev_b64 v[58:59], 1, v[0:1]
	v_lshl_add_u64 v[68:69], v[68:69], 0, v[58:59]
	s_waitcnt lgkmcnt(0)
	v_pk_add_f32 v[6:7], v[6:7], v[8:9]
	s_waitcnt vmcnt(6)
	v_lshlrev_b32_e32 v0, 16, v96
	v_pk_fma_f32 v[6:7], v[6:7], s[38:39], v[236:237] op_sel_hi:[1,0,0]
	v_and_b32_e32 v14, 0xffff0000, v96
	v_mul_f32_e32 v8, 0x4b800000, v7
	v_cmp_gt_f32_e32 vcc, s37, v7
	v_lshlrev_b32_e32 v15, 16, v97
	v_and_b32_e32 v16, 0xffff0000, v97
	v_cndmask_b32_e32 v7, v7, v8, vcc
	v_rsq_f32_e32 v7, v7
	s_waitcnt vmcnt(5)
	v_lshlrev_b32_e32 v17, 16, v94
	v_and_b32_e32 v70, 0xffff0000, v94
	v_lshlrev_b32_e32 v71, 16, v95
	v_mul_f32_e32 v8, 0x45800000, v7
	v_cndmask_b32_e32 v7, v7, v8, vcc
	v_mul_f32_e32 v7, v227, v7
	v_mul_f32_e32 v8, v41, v7
	v_mul_f32_e32 v9, v43, v7
	v_mul_f32_e32 v8, v30, v8
	v_mul_f32_e32 v9, v31, v9
	v_mul_f32_e32 v8, v8, v110
	v_mul_f32_e32 v9, v9, v106
	v_cvt_pk_bf16_f32 v8, v8, v9
	v_mul_f32_e32 v9, v47, v7
	v_mul_f32_e32 v41, v45, v7
	v_mul_f32_e32 v9, v32, v9
	v_mul_f32_e32 v41, v33, v41
	v_mul_f32_e32 v9, v9, v111
	v_mul_f32_e32 v41, v41, v107
	v_cvt_pk_bf16_f32 v9, v9, v41
	global_store_dwordx2 v[68:69], v[8:9], off sc1
	v_mul_f32_e32 v8, v49, v7
	v_mul_f32_e32 v8, v26, v8
	v_mul_f32_e32 v0, v8, v0
	v_mul_f32_e32 v8, v35, v7
	v_mul_f32_e32 v8, v27, v8
	v_mul_f32_e32 v8, v8, v14
	v_cvt_pk_bf16_f32 v8, v0, v8
	v_mul_f32_e32 v0, v39, v7
	v_mul_f32_e32 v9, v37, v7
	v_mul_f32_e32 v0, v28, v0
	v_mul_f32_e32 v9, v29, v9
	v_mul_f32_e32 v0, v0, v15
	v_mul_f32_e32 v9, v9, v16
	v_cvt_pk_bf16_f32 v9, v0, v9
	global_store_dwordx2 v[68:69], v[8:9], off offset:32 sc1
	v_mul_f32_e32 v0, v63, v7
	v_mul_f32_e32 v8, v62, v7
	v_mul_f32_e32 v0, v22, v0
	v_mul_f32_e32 v8, v23, v8
	v_mul_f32_e32 v0, v0, v17
	v_mul_f32_e32 v8, v8, v70
	v_cvt_pk_bf16_f32 v8, v0, v8
	v_mul_f32_e32 v0, v61, v7
	v_mul_f32_e32 v9, v60, v7
	v_and_b32_e32 v72, 0xffff0000, v95
	v_mul_f32_e32 v0, v24, v0
	v_mul_f32_e32 v9, v25, v9
	v_mul_f32_e32 v0, v0, v71
	v_mul_f32_e32 v9, v9, v72
	v_cvt_pk_bf16_f32 v9, v0, v9
	global_store_dwordx2 v[68:69], v[8:9], off offset:64 sc1
	v_mul_f32_e32 v0, v65, v7
	v_mul_f32_e32 v8, v64, v7
	v_mul_f32_e32 v9, 0x4b800000, v6
	v_cmp_gt_f32_e32 vcc, s37, v6
	s_waitcnt vmcnt(7)
	v_lshlrev_b32_e32 v73, 16, v92
	v_and_b32_e32 v74, 0xffff0000, v92
	v_mul_f32_e32 v0, v18, v0
	v_mul_f32_e32 v8, v19, v8
	v_cndmask_b32_e32 v6, v6, v9, vcc
	v_mul_f32_e32 v0, v0, v73
	v_mul_f32_e32 v8, v8, v74
	v_rsq_f32_e32 v6, v6
	v_cvt_pk_bf16_f32 v8, v0, v8
	v_mul_f32_e32 v0, v67, v7
	v_mul_f32_e32 v7, v66, v7
	v_lshlrev_b32_e32 v75, 16, v93
	v_and_b32_e32 v76, 0xffff0000, v93
	v_mul_f32_e32 v0, v20, v0
	v_mul_f32_e32 v7, v21, v7
	v_mul_f32_e32 v0, v0, v75
	v_mul_f32_e32 v7, v7, v76
	v_cvt_pk_bf16_f32 v9, v0, v7
	v_mul_f32_e32 v0, 0x45800000, v6
	v_cndmask_b32_e32 v0, v6, v0, vcc
	v_mul_f32_e32 v0, v227, v0
	v_mul_f32_e32 v6, v40, v0
	v_mul_f32_e32 v6, v30, v6
	s_waitcnt vmcnt(6)
	v_lshlrev_b32_e32 v7, 16, v90
	v_mul_f32_e32 v6, v6, v7
	v_mul_f32_e32 v7, v42, v0
	global_store_dwordx2 v[68:69], v[8:9], off offset:96 sc1
	v_mul_f32_e32 v7, v31, v7
	v_and_b32_e32 v8, 0xffff0000, v90
	v_mul_f32_e32 v7, v7, v8
	v_cvt_pk_bf16_f32 v6, v6, v7
	v_mul_f32_e32 v7, v46, v0
	v_mul_f32_e32 v7, v32, v7
	v_lshlrev_b32_e32 v8, 16, v91
	v_mul_f32_e32 v7, v7, v8
	v_mul_f32_e32 v8, v44, v0
	v_mul_f32_e32 v8, v33, v8
	v_and_b32_e32 v9, 0xffff0000, v91
	v_mul_f32_e32 v8, v8, v9
	v_cvt_pk_bf16_f32 v7, v7, v8
	v_lshl_add_u64 v[8:9], s[16:17], 0, v[56:57]
	v_lshl_add_u64 v[8:9], v[8:9], 0, v[58:59]
	global_store_dwordx2 v[8:9], v[6:7], off sc1
	v_mul_f32_e32 v6, v48, v0
	v_mul_f32_e32 v6, v26, v6
	s_waitcnt vmcnt(7)
	v_lshlrev_b32_e32 v7, 16, v54
	v_mul_f32_e32 v6, v6, v7
	v_mul_f32_e32 v7, v34, v0
	v_mul_f32_e32 v7, v27, v7
	v_and_b32_e32 v14, 0xffff0000, v54
	v_mul_f32_e32 v7, v7, v14
	v_cvt_pk_bf16_f32 v6, v6, v7
	v_mul_f32_e32 v7, v38, v0
	v_mul_f32_e32 v7, v28, v7
	v_lshlrev_b32_e32 v14, 16, v55
	v_mul_f32_e32 v7, v7, v14
	v_mul_f32_e32 v14, v36, v0
	v_mul_f32_e32 v14, v29, v14
	v_and_b32_e32 v15, 0xffff0000, v55
	v_mul_f32_e32 v14, v14, v15
	v_cvt_pk_bf16_f32 v7, v7, v14
	global_store_dwordx2 v[8:9], v[6:7], off offset:32 sc1
	v_mul_f32_e32 v6, v11, v0
	v_mul_f32_e32 v6, v22, v6
	s_waitcnt vmcnt(7)
	v_lshlrev_b32_e32 v7, 16, v52
	v_mul_f32_e32 v6, v6, v7
	v_mul_f32_e32 v7, v10, v0
	v_mul_f32_e32 v7, v23, v7
	v_and_b32_e32 v10, 0xffff0000, v52
	v_mul_f32_e32 v7, v7, v10
	v_cvt_pk_bf16_f32 v6, v6, v7
	v_mul_f32_e32 v7, v13, v0
	v_mul_f32_e32 v7, v24, v7
	v_lshlrev_b32_e32 v10, 16, v53
	v_mul_f32_e32 v7, v7, v10
	v_mul_f32_e32 v10, v12, v0
	v_mul_f32_e32 v10, v25, v10
	v_and_b32_e32 v11, 0xffff0000, v53
	v_mul_f32_e32 v10, v10, v11
	v_cvt_pk_bf16_f32 v7, v7, v10
	v_mul_f32_e32 v3, v3, v0
	global_store_dwordx2 v[8:9], v[6:7], off offset:64 sc1
	v_mul_f32_e32 v3, v18, v3
	s_waitcnt vmcnt(7)
	v_lshlrev_b32_e32 v6, 16, v50
	v_mul_f32_e32 v2, v2, v0
	v_mul_f32_e32 v3, v3, v6
	v_mul_f32_e32 v2, v19, v2
	v_and_b32_e32 v6, 0xffff0000, v50
	v_mul_f32_e32 v2, v2, v6
	v_cvt_pk_bf16_f32 v2, v3, v2
	v_mul_f32_e32 v3, v5, v0
	v_mul_f32_e32 v0, v4, v0
	v_mul_f32_e32 v3, v20, v3
	v_lshlrev_b32_e32 v5, 16, v51
	v_mul_f32_e32 v0, v21, v0
	v_and_b32_e32 v4, 0xffff0000, v51
	v_mul_f32_e32 v3, v3, v5
	v_mul_f32_e32 v0, v0, v4
	v_cvt_pk_bf16_f32 v3, v3, v0
	v_readlane_b32 s50, v255, 30
	v_readlane_b32 s51, v255, 31
	v_readlane_b32 s52, v255, 32
	v_readlane_b32 s53, v255, 33
	v_readlane_b32 s54, v255, 34
	v_readlane_b32 s55, v255, 35
	global_store_dwordx2 v[8:9], v[2:3], off offset:96 sc1

; DI void hgrn_unit(const P& p, int l, int unit, char* lds_all) {
;     ...
;     for (int idx0 = tid512; idx0 < ntok * 16; idx0 += 4 * NT) {
;       float4 a4[4], b4[4];
;       uint2 g4[4];
; #pragma unroll
;       for (int u = 0; u < 4; ++u) {
;         const int idx = idx0 + u * NT;
;         const int tok = idx >> 4, dv4 = idx & 15;
;         const int row = tok < 2048 ? b * 2048 + tok : MLAT + b * 256 + (tok - 2048);
;         a4[u] = *(const float4*)(of + (size_t)tok * 64 + dv4 * 4);
;         b4[u] = *(const float4*)(ob + (size_t)tok * 64 + dv4 * 4);
;         g4[u] = *(const uint2*)(p.G + (size_t)row * 1024 + h * 64 + dv4 * 4);
;       }
; #pragma unroll
;       for (int u = 0; u < 4; ++u) {
;         const int idx = idx0 + u * NT;
;         const int tok = idx >> 4, dv4 = idx & 15;
;         const float o0 = a4[u].x + b4[u].x, o1 = a4[u].y + b4[u].y, o2 = a4[u].z + b4[u].z, o3 = a4[u].w + b4[u].w;
;         float ss = o0 * o0 + o1 * o1 + o2 * o2 + o3 * o3;
;         ss += __shfl_xor(ss, 1);
;         ss += __shfl_xor(ss, 2);
;         ss += __shfl_xor(ss, 4);
;         ss += __shfl_xor(ss, 8);
;         const float rinv = rsqrtf(ss * (1.f / 64.f) + 1e-6f);
.LBB0_940:
	v_ashrrev_i32_e32 v14, 4, v98
	v_add_u32_e32 v17, 0x200, v98
	v_mov_b32_e32 v13, s24
	v_mov_b32_e32 v16, s26
	v_add_u32_e32 v19, 0x400, v98
	v_cmp_gt_i32_e32 vcc, s30, v14
	v_ashrrev_i32_e32 v18, 4, v17
	v_add_u32_e32 v21, 0x600, v98
	v_cndmask_b32_e32 v23, v13, v16, vcc
	v_ashrrev_i32_e32 v20, 4, v19
	v_cmp_gt_i32_e32 vcc, s30, v18
	v_and_b32_e32 v2, 60, v12
	v_ashrrev_i32_e32 v22, 4, v21
	v_cndmask_b32_e32 v32, v13, v16, vcc
	v_cmp_gt_i32_e32 vcc, s30, v20
	v_mov_b32_e32 v7, v1
	v_lshlrev_b32_e32 v0, 2, v2
	v_lshlrev_b32_e32 v6, 1, v2
	v_ashrrev_i32_e32 v15, 31, v14
	v_cndmask_b32_e32 v33, v13, v16, vcc
	v_cmp_gt_i32_e32 vcc, s30, v22
	v_lshl_add_u64 v[24:25], s[42:43], 0, v[0:1]
	v_lshl_add_u64 v[50:51], s[46:47], 0, v[6:7]
	v_add_u32_e32 v6, v23, v14
	v_lshlrev_b64 v[28:29], 8, v[14:15]
	v_ashrrev_i32_e32 v19, 31, v18
	v_ashrrev_i32_e32 v21, 31, v20
	v_cndmask_b32_e32 v13, v13, v16, vcc
	v_ashrrev_i32_e32 v23, 31, v22
	v_lshl_add_u64 v[26:27], s[44:45], 0, v[0:1]
	v_lshl_add_u64 v[30:31], v[24:25], 0, v[28:29]
	v_add_u32_e32 v32, v32, v18
	v_lshlrev_b64 v[18:19], 8, v[18:19]
	v_add_u32_e32 v34, v33, v20
	v_lshlrev_b64 v[20:21], 8, v[20:21]
	v_add_u32_e32 v36, v13, v22
	v_lshlrev_b64 v[22:23], 8, v[22:23]
	global_load_dwordx4 v[14:17], v0, s[0:1]
	v_lshl_add_u64 v[28:29], v[26:27], 0, v[28:29]
	v_ashrrev_i32_e32 v7, 31, v6
	v_lshl_add_u64 v[40:41], v[24:25], 0, v[18:19]
	v_lshl_add_u64 v[42:43], v[26:27], 0, v[18:19]
	v_lshl_add_u64 v[44:45], v[24:25], 0, v[20:21]
	v_lshl_add_u64 v[46:47], v[26:27], 0, v[20:21]
	v_lshl_add_u64 v[48:49], v[24:25], 0, v[22:23]
	v_lshl_add_u64 v[52:53], v[26:27], 0, v[22:23]
	global_load_dwordx4 v[18:21], v[30:31], off
	global_load_dwordx4 v[22:25], v[28:29], off
	v_lshlrev_b64 v[38:39], 11, v[6:7]
	v_ashrrev_i32_e32 v33, 31, v32
	v_ashrrev_i32_e32 v35, 31, v34
	v_ashrrev_i32_e32 v37, 31, v36
	v_lshl_add_u64 v[54:55], v[50:51], 0, v[38:39]
	v_lshlrev_b64 v[56:57], 11, v[32:33]
	v_lshlrev_b64 v[58:59], 11, v[34:35]
	v_lshlrev_b64 v[6:7], 11, v[36:37]
	v_lshl_add_u64 v[60:61], s[16:17], 0, v[38:39]
	global_load_dwordx4 v[26:29], v[40:41], off
	global_load_dwordx4 v[30:33], v[42:43], off
	global_load_dwordx4 v[34:37], v[44:45], off
	s_nop 0
	global_load_dwordx4 v[38:41], v[46:47], off
	global_load_dwordx4 v[42:45], v[48:49], off
	s_nop 0
	global_load_dwordx4 v[46:49], v[52:53], off
	s_nop 0
	global_load_dwordx2 v[52:53], v[54:55], off
	s_mov_b32 s50, 0x358637bd
	v_mov_b64_e32 v[4:5], s[50:51]
	v_or_b32_e32 v2, s2, v2
	v_mov_b32_e32 v3, v1
	v_lshlrev_b32_e32 v2, 1, v2
	v_lshl_add_u64 v[54:55], v[50:51], 0, v[56:57]
	v_lshl_add_u64 v[62:63], v[50:51], 0, v[58:59]
	v_lshl_add_u64 v[50:51], v[50:51], 0, v[6:7]
	v_lshl_add_u64 v[60:61], v[60:61], 0, v[2:3]
	global_load_dwordx2 v[54:55], v[54:55], off
	s_nop 0
	global_load_dwordx2 v[62:63], v[62:63], off
	s_nop 0
	global_load_dwordx2 v[50:51], v[50:51], off
	v_add_u32_e32 v98, 0x800, v98
	v_lshl_add_u64 v[6:7], s[16:17], 0, v[6:7]
	v_add_u32_e32 v12, 0x2000, v12
	s_waitcnt vmcnt(10)
	v_pk_add_f32 v[18:19], v[18:19], v[22:23]
	v_pk_add_f32 v[20:21], v[20:21], v[24:25]
	v_pk_mul_f32 v[22:23], v[18:19], v[18:19]
	v_pk_mul_f32 v[24:25], v[20:21], v[20:21]
	s_waitcnt vmcnt(8)
	v_pk_add_f32 v[26:27], v[26:27], v[30:31]
	v_pk_add_f32 v[28:29], v[28:29], v[32:33]
	v_pk_mul_f32 v[30:31], v[26:27], v[26:27]
	v_pk_mul_f32 v[32:33], v[28:29], v[28:29]
	v_mov_b32_e32 v65, v24
	s_waitcnt vmcnt(3)
	v_lshlrev_b32_e32 v13, 16, v52
	v_and_b32_e32 v66, 0xffff0000, v52
	v_lshlrev_b32_e32 v67, 16, v53
	v_and_b32_e32 v68, 0xffff0000, v53
	v_mov_b32_e32 v53, v22
	v_mov_b32_e32 v52, v30
	v_mov_b32_e32 v22, v31
	v_mov_b32_e32 v64, v32
	v_pk_add_f32 v[22:23], v[52:53], v[22:23]
	v_mov_b32_e32 v24, v33
	v_pk_add_f32 v[22:23], v[22:23], v[64:65]
	s_nop 0
	v_pk_add_f32 v[22:23], v[22:23], v[24:25]
	ds_bpermute_b32 v25, v8, v23
	ds_bpermute_b32 v24, v8, v22
	s_waitcnt lgkmcnt(0)
	v_pk_add_f32 v[22:23], v[22:23], v[24:25]
	ds_bpermute_b32 v25, v9, v23
	ds_bpermute_b32 v24, v9, v22
	s_waitcnt lgkmcnt(0)
	v_pk_add_f32 v[22:23], v[22:23], v[24:25]
	ds_bpermute_b32 v25, v10, v23
	ds_bpermute_b32 v24, v10, v22
	s_waitcnt lgkmcnt(0)
	v_pk_add_f32 v[22:23], v[22:23], v[24:25]
	ds_bpermute_b32 v25, v11, v23
	ds_bpermute_b32 v24, v11, v22
	s_waitcnt lgkmcnt(0)
; DI float bflo(unsigned w) { return __uint_as_float(w << 16); }
; DI float bfhi(unsigned w) { return __uint_as_float(w & 0xffff0000u); }
; DI void hgrn_unit(const P& p, int l, int unit, char* lds_all) {
;     ...
;       for (int u = 0; u < 4; ++u) {
;         const int idx = idx0 + u * NT;
;         const int tok = idx >> 4, dv4 = idx & 15;
;         const float o0 = a4[u].x + b4[u].x, o1 = a4[u].y + b4[u].y, o2 = a4[u].z + b4[u].z, o3 = a4[u].w + b4[u].w;
;         float ss = o0 * o0 + o1 * o1 + o2 * o2 + o3 * o3;
;         ss += __shfl_xor(ss, 1);
;         ss += __shfl_xor(ss, 2);
;         ss += __shfl_xor(ss, 4);
;         ss += __shfl_xor(ss, 8);
;         const float rinv = rsqrtf(ss * (1.f / 64.f) + 1e-6f);
;         const int row = tok < 2048 ? b * 2048 + tok : MLAT + b * 256 + (tok - 2048);
;         const int col = h * 64 + dv4 * 4;
;         const float4 n4 = *(const float4*)(ng + dv4 * 4);
;         uint2 o;
;         o.x = pack2(o0 * rinv * n4.x * bflo(g4[u].x), o1 * rinv * n4.y * bfhi(g4[u].x));
;         o.y = pack2(o2 * rinv * n4.z * bflo(g4[u].y), o3 * rinv * n4.w * bfhi(g4[u].y));
;         *(uint2*)(p.H + (size_t)row * 1024 + col) = o;
;       }
;     }
	v_pk_add_f32 v[22:23], v[22:23], v[24:25]
	s_nop 0
	v_pk_fma_f32 v[22:23], v[22:23], s[38:39], v[4:5] op_sel_hi:[1,0,0]
	s_nop 0
	v_mul_f32_e32 v24, 0x4b800000, v23
	v_cmp_gt_f32_e32 vcc, s37, v23
	s_nop 1
	v_cndmask_b32_e32 v23, v23, v24, vcc
	v_rsq_f32_e32 v23, v23
	s_nop 0
	v_mul_f32_e32 v24, 0x45800000, v23
	v_cndmask_b32_e32 v23, v23, v24, vcc
	v_mul_f32_e32 v18, v18, v23
	v_mul_f32_e32 v19, v19, v23
	v_mul_f32_e32 v20, v20, v23
	v_mul_f32_e32 v21, v21, v23
	v_mul_f32_e32 v14, v14, v18
	v_mul_f32_e32 v15, v15, v19
	v_mul_f32_e32 v16, v16, v20
	v_mul_f32_e32 v17, v17, v21
	v_mul_f32_e32 v13, v14, v13
	v_mul_f32_e32 v14, v15, v66
	v_mul_f32_e32 v15, v16, v67
	v_mul_f32_e32 v16, v17, v68
	v_cvt_pk_bf16_f32 v14, v13, v14
	v_cvt_pk_bf16_f32 v15, v15, v16
	global_store_dwordx2 v[60:61], v[14:15], off sc1
	global_load_dwordx4 v[14:17], v0, s[0:1]
	v_mul_f32_e32 v24, 0x4b800000, v22
	v_cmp_gt_f32_e32 vcc, s37, v22
	s_waitcnt vmcnt(4)
	v_lshlrev_b32_e32 v13, 16, v54
	v_and_b32_e32 v20, 0xffff0000, v54
	v_cndmask_b32_e32 v22, v22, v24, vcc
	v_rsq_f32_e32 v22, v22
	v_lshlrev_b32_e32 v21, 16, v55
	v_and_b32_e32 v23, 0xffff0000, v55
	v_lshl_add_u64 v[18:19], s[16:17], 0, v[56:57]
	v_mul_f32_e32 v24, 0x45800000, v22
	v_cndmask_b32_e32 v22, v22, v24, vcc
	v_mul_f32_e32 v24, v26, v22
	v_mul_f32_e32 v25, v27, v22
	v_mul_f32_e32 v26, v28, v22
	v_mul_f32_e32 v22, v29, v22
	v_lshl_add_u64 v[18:19], v[18:19], 0, v[2:3]
	s_waitcnt vmcnt(0)
	v_mul_f32_e32 v14, v14, v24
	v_mul_f32_e32 v15, v15, v25
	v_mul_f32_e32 v16, v16, v26
	v_mul_f32_e32 v17, v17, v22
	v_mul_f32_e32 v13, v14, v13
	v_mul_f32_e32 v14, v15, v20
	v_mul_f32_e32 v15, v16, v21
	v_mul_f32_e32 v16, v17, v23
	v_cvt_pk_bf16_f32 v14, v13, v14
	v_cvt_pk_bf16_f32 v15, v15, v16
	global_store_dwordx2 v[18:19], v[14:15], off sc1
	global_load_dwordx4 v[14:17], v0, s[0:1]
	v_pk_add_f32 v[20:21], v[34:35], v[38:39]
	v_pk_add_f32 v[24:25], v[42:43], v[46:47]
	v_pk_add_f32 v[22:23], v[36:37], v[40:41]
	v_pk_add_f32 v[26:27], v[44:45], v[48:49]
	v_pk_mul_f32 v[28:29], v[20:21], v[20:21]
	v_pk_mul_f32 v[32:33], v[24:25], v[24:25]
	v_pk_mul_f32 v[30:31], v[22:23], v[22:23]
	v_pk_mul_f32 v[34:35], v[26:27], v[26:27]
	v_mov_b32_e32 v36, v32
	v_mov_b32_e32 v37, v28
	v_mov_b32_e32 v28, v33
	v_mov_b32_e32 v32, v34
	v_mov_b32_e32 v33, v30
	v_pk_add_f32 v[28:29], v[36:37], v[28:29]
	v_mov_b32_e32 v30, v35
	v_pk_add_f32 v[28:29], v[28:29], v[32:33]
	v_lshlrev_b32_e32 v13, 16, v62
	v_pk_add_f32 v[28:29], v[28:29], v[30:31]
	ds_bpermute_b32 v31, v8, v29
	ds_bpermute_b32 v30, v8, v28
	v_and_b32_e32 v38, 0xffff0000, v62
	v_lshlrev_b32_e32 v39, 16, v63
	v_and_b32_e32 v40, 0xffff0000, v63
	v_lshl_add_u64 v[18:19], s[16:17], 0, v[58:59]
	s_waitcnt lgkmcnt(0)
	v_pk_add_f32 v[28:29], v[28:29], v[30:31]
	ds_bpermute_b32 v31, v9, v29
	ds_bpermute_b32 v30, v9, v28
	v_lshl_add_u64 v[18:19], v[18:19], 0, v[2:3]
	v_lshl_add_u64 v[2:3], v[6:7], 0, v[2:3]
	v_lshlrev_b32_e32 v6, 16, v51
	v_and_b32_e32 v7, 0xffff0000, v51
	s_waitcnt lgkmcnt(0)
	v_pk_add_f32 v[28:29], v[28:29], v[30:31]
	ds_bpermute_b32 v31, v10, v29
	ds_bpermute_b32 v30, v10, v28
	s_waitcnt lgkmcnt(0)
	v_pk_add_f32 v[28:29], v[28:29], v[30:31]
	ds_bpermute_b32 v31, v11, v29
	ds_bpermute_b32 v30, v11, v28
	s_waitcnt lgkmcnt(0)
	v_pk_add_f32 v[28:29], v[28:29], v[30:31]
	s_nop 0
	v_pk_fma_f32 v[4:5], v[28:29], s[38:39], v[4:5] op_sel_hi:[1,0,0]
	s_nop 0
	v_mul_f32_e32 v28, 0x4b800000, v5
	v_cmp_gt_f32_e32 vcc, s37, v5
	s_nop 1
	v_cndmask_b32_e32 v5, v5, v28, vcc
	v_rsq_f32_e32 v5, v5
	s_nop 0
	v_mul_f32_e32 v28, 0x45800000, v5
	v_cndmask_b32_e32 v5, v5, v28, vcc
	v_mul_f32_e32 v20, v20, v5
	v_mul_f32_e32 v21, v21, v5
	v_mul_f32_e32 v22, v22, v5
	v_mul_f32_e32 v5, v23, v5
	v_cmp_le_i32_e32 vcc, s25, v98
	s_or_b64 s[48:49], vcc, s[48:49]
	v_cmp_gt_f32_e32 vcc, s37, v4
	s_waitcnt vmcnt(0)
	v_mul_f32_e32 v14, v14, v20
	v_mul_f32_e32 v15, v15, v21
	v_mul_f32_e32 v16, v16, v22
	v_mul_f32_e32 v5, v17, v5
	v_mul_f32_e32 v13, v14, v13
	v_mul_f32_e32 v14, v15, v38
	v_mul_f32_e32 v15, v16, v39
	v_mul_f32_e32 v5, v5, v40
	v_cvt_pk_bf16_f32 v14, v13, v14
	v_cvt_pk_bf16_f32 v15, v15, v5
	global_store_dwordx2 v[18:19], v[14:15], off sc1
	global_load_dwordx4 v[14:17], v0, s[0:1]
	v_mul_f32_e32 v13, 0x4b800000, v4
	v_cndmask_b32_e32 v4, v4, v13, vcc
	v_rsq_f32_e32 v4, v4
	v_lshlrev_b32_e32 v0, 16, v50
	v_and_b32_e32 v5, 0xffff0000, v50
	v_mul_f32_e32 v13, 0x45800000, v4
	v_cndmask_b32_e32 v4, v4, v13, vcc
	v_mul_f32_e32 v13, v24, v4
	v_mul_f32_e32 v18, v25, v4
	v_mul_f32_e32 v19, v26, v4
	v_mul_f32_e32 v4, v27, v4
	s_waitcnt vmcnt(0)
	v_mul_f32_e32 v13, v14, v13
	v_mul_f32_e32 v14, v15, v18
	v_mul_f32_e32 v15, v16, v19
	v_mul_f32_e32 v4, v17, v4
	v_mul_f32_e32 v0, v13, v0
	v_mul_f32_e32 v5, v14, v5
	v_mul_f32_e32 v6, v15, v6
	v_mul_f32_e32 v7, v4, v7
	v_cvt_pk_bf16_f32 v4, v0, v5
	v_cvt_pk_bf16_f32 v5, v6, v7
	global_store_dwordx2 v[2:3], v[4:5], off sc1
	s_andn2_b64 exec, exec, s[48:49]
	s_cbranch_execnz .LBB0_940
	s_branch .LBB0_814
